# v59 + FFN-up SwiGLU epilogue rewritten with packed f32 VALU (v_pk_mul/v_pk_fma), same math
# speedup vs baseline: 1.0101x; 1.0101x over previous
.LBB0_117:
	v_lshl_add_u32 v138, s53, 10, v152
	ds_read2_b32 v[148:149], v138 offset1:16
	ds_read2_b32 v[146:147], v138 offset0:32 offset1:48
	ds_read2_b32 v[144:145], v138 offset0:128 offset1:144
	ds_read2_b32 v[138:139], v138 offset0:160 offset1:176
	s_add_u32 s0, s20, 0xffffff00
	s_addc_u32 s1, s21, -1
	v_readlane_b32 s20, v209, 45
	v_readlane_b32 s21, v209, 46
	v_lshl_or_b32 v142, s52, 7, v153
	v_lshl_add_u32 v155, s54, 8, v150
	v_ashrrev_i32_e32 v143, 31, v142
	v_lshlrev_b64 v[142:143], 1, v[142:143]
	v_lshl_add_u64 v[142:143], v[142:143], 0, s[20:21]
	v_mad_i64_i32 v[142:143], vcc, v155, s68, v[142:143]
	s_lshl_b32 s20, s68, 7
	s_mov_b32 s21, 0
	v_lshl_add_u64 v[172:173], v[142:143], 0, s[20:21]
	s_lshl_b32 s20, s68, 4
	s_waitcnt lgkmcnt(0)
	v_cmp_gt_f32_e32 vcc, 0x800000, v148
	v_mul_f32_e32 v141, 0x4b800000, v148
	v_pk_mul_f32 v[164:165], v[124:125], v[92:93]
	v_cndmask_b32_e32 v141, v148, v141, vcc
	v_pk_mul_f32 v[166:167], v[126:127], v[94:95]
	v_rsq_f32_e32 v141, v141
	v_pk_mul_f32 v[168:169], v[120:121], v[88:89]
	v_pk_mul_f32 v[170:171], v[122:123], v[90:91]
	v_mul_f32_e32 v140, 0x45800000, v141
	v_cndmask_b32_e32 v140, v141, v140, vcc
	v_mul_f32_e32 v140, 0xbfb8aa3b, v140
	v_pk_mul_f32 v[156:157], v[124:125], v[140:141] op_sel_hi:[1,0]
	v_pk_mul_f32 v[158:159], v[126:127], v[140:141] op_sel_hi:[1,0]
	v_pk_mul_f32 v[160:161], v[120:121], v[140:141] op_sel_hi:[1,0]
	v_pk_mul_f32 v[162:163], v[122:123], v[140:141] op_sel_hi:[1,0]
	v_exp_f32_e32 v156, v156
	v_exp_f32_e32 v157, v157
	v_exp_f32_e32 v158, v158
	v_exp_f32_e32 v159, v159
	v_exp_f32_e32 v160, v160
	v_exp_f32_e32 v161, v161
	v_exp_f32_e32 v162, v162
	v_exp_f32_e32 v163, v163
	v_pk_fma_f32 v[156:157], v[156:157], v[148:149], v[148:149] op_sel_hi:[1,0,0]
	v_pk_fma_f32 v[158:159], v[158:159], v[148:149], v[148:149] op_sel_hi:[1,0,0]
	v_pk_fma_f32 v[160:161], v[160:161], v[148:149], v[148:149] op_sel_hi:[1,0,0]
	v_pk_fma_f32 v[162:163], v[162:163], v[148:149], v[148:149] op_sel_hi:[1,0,0]
	v_rcp_f32_e32 v156, v156
	v_rcp_f32_e32 v157, v157
	v_rcp_f32_e32 v158, v158
	v_rcp_f32_e32 v159, v159
	v_rcp_f32_e32 v160, v160
	v_rcp_f32_e32 v161, v161
	v_rcp_f32_e32 v162, v162
	v_rcp_f32_e32 v163, v163
	v_pk_mul_f32 v[164:165], v[164:165], v[156:157]
	v_pk_mul_f32 v[166:167], v[166:167], v[158:159]
	v_pk_mul_f32 v[168:169], v[168:169], v[160:161]
	v_pk_mul_f32 v[170:171], v[170:171], v[162:163]
	v_cvt_pk_bf16_f32 v164, v164, v165
	v_cvt_pk_bf16_f32 v165, v166, v167
	v_cvt_pk_bf16_f32 v166, v168, v169
	v_cvt_pk_bf16_f32 v167, v170, v171
	global_store_dwordx4 v[142:143], v[164:167], off
	v_cmp_gt_f32_e32 vcc, 0x800000, v149
	v_mul_f32_e32 v141, 0x4b800000, v149
	v_pk_mul_f32 v[164:165], v[116:117], v[84:85]
	v_cndmask_b32_e32 v141, v149, v141, vcc
	v_pk_mul_f32 v[166:167], v[118:119], v[86:87]
	v_rsq_f32_e32 v141, v141
	v_pk_mul_f32 v[168:169], v[112:113], v[80:81]
	v_pk_mul_f32 v[170:171], v[114:115], v[82:83]
	v_mul_f32_e32 v140, 0x45800000, v141
	v_cndmask_b32_e32 v140, v141, v140, vcc
	v_mul_f32_e32 v140, 0xbfb8aa3b, v140
	v_pk_mul_f32 v[156:157], v[116:117], v[140:141] op_sel_hi:[1,0]
	v_pk_mul_f32 v[158:159], v[118:119], v[140:141] op_sel_hi:[1,0]
	v_pk_mul_f32 v[160:161], v[112:113], v[140:141] op_sel_hi:[1,0]
	v_pk_mul_f32 v[162:163], v[114:115], v[140:141] op_sel_hi:[1,0]
	v_exp_f32_e32 v156, v156
	v_exp_f32_e32 v157, v157
	v_exp_f32_e32 v158, v158
	v_exp_f32_e32 v159, v159
	v_exp_f32_e32 v160, v160
	v_exp_f32_e32 v161, v161
	v_exp_f32_e32 v162, v162
	v_exp_f32_e32 v163, v163
	v_pk_fma_f32 v[156:157], v[156:157], v[148:149], v[148:149] op_sel:[0,1,1] op_sel_hi:[1,1,1]
	v_pk_fma_f32 v[158:159], v[158:159], v[148:149], v[148:149] op_sel:[0,1,1] op_sel_hi:[1,1,1]
	v_pk_fma_f32 v[160:161], v[160:161], v[148:149], v[148:149] op_sel:[0,1,1] op_sel_hi:[1,1,1]
	v_pk_fma_f32 v[162:163], v[162:163], v[148:149], v[148:149] op_sel:[0,1,1] op_sel_hi:[1,1,1]
	v_rcp_f32_e32 v156, v156
	v_rcp_f32_e32 v157, v157
	v_rcp_f32_e32 v158, v158
	v_rcp_f32_e32 v159, v159
	v_rcp_f32_e32 v160, v160
	v_rcp_f32_e32 v161, v161
	v_rcp_f32_e32 v162, v162
	v_rcp_f32_e32 v163, v163
	v_lshl_add_u64 v[142:143], v[142:143], 0, s[20:21]
	v_pk_mul_f32 v[164:165], v[164:165], v[156:157]
	v_pk_mul_f32 v[166:167], v[166:167], v[158:159]
	v_pk_mul_f32 v[168:169], v[168:169], v[160:161]
	v_pk_mul_f32 v[170:171], v[170:171], v[162:163]
	v_cvt_pk_bf16_f32 v164, v164, v165
	v_cvt_pk_bf16_f32 v165, v166, v167
	v_cvt_pk_bf16_f32 v166, v168, v169
	v_cvt_pk_bf16_f32 v167, v170, v171
	global_store_dwordx4 v[142:143], v[164:167], off
	v_cmp_gt_f32_e32 vcc, 0x800000, v146
	v_mul_f32_e32 v141, 0x4b800000, v146
	v_pk_mul_f32 v[164:165], v[108:109], v[76:77]
	v_cndmask_b32_e32 v141, v146, v141, vcc
	v_pk_mul_f32 v[166:167], v[110:111], v[78:79]
	v_rsq_f32_e32 v141, v141
	v_pk_mul_f32 v[168:169], v[104:105], v[72:73]
	v_pk_mul_f32 v[170:171], v[106:107], v[74:75]
	v_mul_f32_e32 v140, 0x45800000, v141
	v_cndmask_b32_e32 v140, v141, v140, vcc
	v_mul_f32_e32 v140, 0xbfb8aa3b, v140
	v_pk_mul_f32 v[156:157], v[108:109], v[140:141] op_sel_hi:[1,0]
	v_pk_mul_f32 v[158:159], v[110:111], v[140:141] op_sel_hi:[1,0]
	v_pk_mul_f32 v[160:161], v[104:105], v[140:141] op_sel_hi:[1,0]
	v_pk_mul_f32 v[162:163], v[106:107], v[140:141] op_sel_hi:[1,0]
	v_exp_f32_e32 v156, v156
	v_exp_f32_e32 v157, v157
	v_exp_f32_e32 v158, v158
	v_exp_f32_e32 v159, v159
	v_exp_f32_e32 v160, v160
	v_exp_f32_e32 v161, v161
	v_exp_f32_e32 v162, v162
	v_exp_f32_e32 v163, v163
	v_pk_fma_f32 v[156:157], v[156:157], v[146:147], v[146:147] op_sel_hi:[1,0,0]
	v_pk_fma_f32 v[158:159], v[158:159], v[146:147], v[146:147] op_sel_hi:[1,0,0]
	v_pk_fma_f32 v[160:161], v[160:161], v[146:147], v[146:147] op_sel_hi:[1,0,0]
	v_pk_fma_f32 v[162:163], v[162:163], v[146:147], v[146:147] op_sel_hi:[1,0,0]
	v_rcp_f32_e32 v156, v156
	v_rcp_f32_e32 v157, v157
	v_rcp_f32_e32 v158, v158
	v_rcp_f32_e32 v159, v159
	v_rcp_f32_e32 v160, v160
	v_rcp_f32_e32 v161, v161
	v_rcp_f32_e32 v162, v162
	v_rcp_f32_e32 v163, v163
	v_lshl_add_u64 v[142:143], v[142:143], 0, s[20:21]
	v_pk_mul_f32 v[164:165], v[164:165], v[156:157]
	v_pk_mul_f32 v[166:167], v[166:167], v[158:159]
	v_pk_mul_f32 v[168:169], v[168:169], v[160:161]
	v_pk_mul_f32 v[170:171], v[170:171], v[162:163]
	v_cvt_pk_bf16_f32 v164, v164, v165
	v_cvt_pk_bf16_f32 v165, v166, v167
	v_cvt_pk_bf16_f32 v166, v168, v169
	v_cvt_pk_bf16_f32 v167, v170, v171
	global_store_dwordx4 v[142:143], v[164:167], off
	v_cmp_gt_f32_e32 vcc, 0x800000, v147
	v_mul_f32_e32 v141, 0x4b800000, v147
	v_pk_mul_f32 v[164:165], v[100:101], v[68:69]
	v_cndmask_b32_e32 v141, v147, v141, vcc
	v_pk_mul_f32 v[166:167], v[102:103], v[70:71]
	v_rsq_f32_e32 v141, v141
	v_pk_mul_f32 v[168:169], v[96:97], v[64:65]
	v_pk_mul_f32 v[170:171], v[98:99], v[66:67]
	v_mul_f32_e32 v140, 0x45800000, v141
	v_cndmask_b32_e32 v140, v141, v140, vcc
	v_mul_f32_e32 v140, 0xbfb8aa3b, v140
	v_pk_mul_f32 v[156:157], v[100:101], v[140:141] op_sel_hi:[1,0]
	v_pk_mul_f32 v[158:159], v[102:103], v[140:141] op_sel_hi:[1,0]
	v_pk_mul_f32 v[160:161], v[96:97], v[140:141] op_sel_hi:[1,0]
	v_pk_mul_f32 v[162:163], v[98:99], v[140:141] op_sel_hi:[1,0]
	v_exp_f32_e32 v156, v156
	v_exp_f32_e32 v157, v157
	v_exp_f32_e32 v158, v158
	v_exp_f32_e32 v159, v159
	v_exp_f32_e32 v160, v160
	v_exp_f32_e32 v161, v161
	v_exp_f32_e32 v162, v162
	v_exp_f32_e32 v163, v163
	v_pk_fma_f32 v[156:157], v[156:157], v[146:147], v[146:147] op_sel:[0,1,1] op_sel_hi:[1,1,1]
	v_pk_fma_f32 v[158:159], v[158:159], v[146:147], v[146:147] op_sel:[0,1,1] op_sel_hi:[1,1,1]
	v_pk_fma_f32 v[160:161], v[160:161], v[146:147], v[146:147] op_sel:[0,1,1] op_sel_hi:[1,1,1]
	v_pk_fma_f32 v[162:163], v[162:163], v[146:147], v[146:147] op_sel:[0,1,1] op_sel_hi:[1,1,1]
	v_rcp_f32_e32 v156, v156
	v_rcp_f32_e32 v157, v157
	v_rcp_f32_e32 v158, v158
	v_rcp_f32_e32 v159, v159
	v_rcp_f32_e32 v160, v160
	v_rcp_f32_e32 v161, v161
	v_rcp_f32_e32 v162, v162
	v_rcp_f32_e32 v163, v163
	v_lshl_add_u64 v[142:143], v[142:143], 0, s[20:21]
	v_pk_mul_f32 v[164:165], v[164:165], v[156:157]
	v_pk_mul_f32 v[166:167], v[166:167], v[158:159]
	v_pk_mul_f32 v[168:169], v[168:169], v[160:161]
	v_pk_mul_f32 v[170:171], v[170:171], v[162:163]
	v_cvt_pk_bf16_f32 v164, v164, v165
	v_cvt_pk_bf16_f32 v165, v166, v167
	v_cvt_pk_bf16_f32 v166, v168, v169
	v_cvt_pk_bf16_f32 v167, v170, v171
	global_store_dwordx4 v[142:143], v[164:167], off
	v_cmp_gt_f32_e32 vcc, 0x800000, v144
	v_mul_f32_e32 v141, 0x4b800000, v144
	v_pk_mul_f32 v[164:165], v[60:61], v[28:29]
	v_cndmask_b32_e32 v141, v144, v141, vcc
	v_pk_mul_f32 v[166:167], v[62:63], v[30:31]
	v_rsq_f32_e32 v141, v141
	v_pk_mul_f32 v[168:169], v[56:57], v[24:25]
	v_pk_mul_f32 v[170:171], v[58:59], v[26:27]
	v_mul_f32_e32 v140, 0x45800000, v141
	v_cndmask_b32_e32 v140, v141, v140, vcc
	v_mul_f32_e32 v140, 0xbfb8aa3b, v140
	v_pk_mul_f32 v[156:157], v[60:61], v[140:141] op_sel_hi:[1,0]
	v_pk_mul_f32 v[158:159], v[62:63], v[140:141] op_sel_hi:[1,0]
	v_pk_mul_f32 v[160:161], v[56:57], v[140:141] op_sel_hi:[1,0]
	v_pk_mul_f32 v[162:163], v[58:59], v[140:141] op_sel_hi:[1,0]
	v_exp_f32_e32 v156, v156
	v_exp_f32_e32 v157, v157
	v_exp_f32_e32 v158, v158
	v_exp_f32_e32 v159, v159
	v_exp_f32_e32 v160, v160
	v_exp_f32_e32 v161, v161
	v_exp_f32_e32 v162, v162
	v_exp_f32_e32 v163, v163
	v_pk_fma_f32 v[156:157], v[156:157], v[144:145], v[144:145] op_sel_hi:[1,0,0]
	v_pk_fma_f32 v[158:159], v[158:159], v[144:145], v[144:145] op_sel_hi:[1,0,0]
	v_pk_fma_f32 v[160:161], v[160:161], v[144:145], v[144:145] op_sel_hi:[1,0,0]
	v_pk_fma_f32 v[162:163], v[162:163], v[144:145], v[144:145] op_sel_hi:[1,0,0]
	v_rcp_f32_e32 v156, v156
	v_rcp_f32_e32 v157, v157
	v_rcp_f32_e32 v158, v158
	v_rcp_f32_e32 v159, v159
	v_rcp_f32_e32 v160, v160
	v_rcp_f32_e32 v161, v161
	v_rcp_f32_e32 v162, v162
	v_rcp_f32_e32 v163, v163
	v_pk_mul_f32 v[164:165], v[164:165], v[156:157]
	v_pk_mul_f32 v[166:167], v[166:167], v[158:159]
	v_pk_mul_f32 v[168:169], v[168:169], v[160:161]
	v_pk_mul_f32 v[170:171], v[170:171], v[162:163]
	v_cvt_pk_bf16_f32 v164, v164, v165
	v_cvt_pk_bf16_f32 v165, v166, v167
	v_cvt_pk_bf16_f32 v166, v168, v169
	v_cvt_pk_bf16_f32 v167, v170, v171
	global_store_dwordx4 v[172:173], v[164:167], off
	v_cmp_gt_f32_e32 vcc, 0x800000, v145
	v_mul_f32_e32 v141, 0x4b800000, v145
	v_pk_mul_f32 v[164:165], v[52:53], v[20:21]
	v_cndmask_b32_e32 v141, v145, v141, vcc
	v_pk_mul_f32 v[166:167], v[54:55], v[22:23]
	v_rsq_f32_e32 v141, v141
	v_pk_mul_f32 v[168:169], v[48:49], v[16:17]
	v_pk_mul_f32 v[170:171], v[50:51], v[18:19]
	v_mul_f32_e32 v140, 0x45800000, v141
	v_cndmask_b32_e32 v140, v141, v140, vcc
	v_mul_f32_e32 v140, 0xbfb8aa3b, v140
	v_pk_mul_f32 v[156:157], v[52:53], v[140:141] op_sel_hi:[1,0]
	v_pk_mul_f32 v[158:159], v[54:55], v[140:141] op_sel_hi:[1,0]
	v_pk_mul_f32 v[160:161], v[48:49], v[140:141] op_sel_hi:[1,0]
	v_pk_mul_f32 v[162:163], v[50:51], v[140:141] op_sel_hi:[1,0]
	v_exp_f32_e32 v156, v156
	v_exp_f32_e32 v157, v157
	v_exp_f32_e32 v158, v158
	v_exp_f32_e32 v159, v159
	v_exp_f32_e32 v160, v160
	v_exp_f32_e32 v161, v161
	v_exp_f32_e32 v162, v162
	v_exp_f32_e32 v163, v163
	v_pk_fma_f32 v[156:157], v[156:157], v[144:145], v[144:145] op_sel:[0,1,1] op_sel_hi:[1,1,1]
	v_pk_fma_f32 v[158:159], v[158:159], v[144:145], v[144:145] op_sel:[0,1,1] op_sel_hi:[1,1,1]
	v_pk_fma_f32 v[160:161], v[160:161], v[144:145], v[144:145] op_sel:[0,1,1] op_sel_hi:[1,1,1]
	v_pk_fma_f32 v[162:163], v[162:163], v[144:145], v[144:145] op_sel:[0,1,1] op_sel_hi:[1,1,1]
	v_rcp_f32_e32 v156, v156
	v_rcp_f32_e32 v157, v157
	v_rcp_f32_e32 v158, v158
	v_rcp_f32_e32 v159, v159
	v_rcp_f32_e32 v160, v160
	v_rcp_f32_e32 v161, v161
	v_rcp_f32_e32 v162, v162
	v_rcp_f32_e32 v163, v163
	v_lshl_add_u64 v[172:173], v[172:173], 0, s[20:21]
	v_pk_mul_f32 v[164:165], v[164:165], v[156:157]
	v_pk_mul_f32 v[166:167], v[166:167], v[158:159]
	v_pk_mul_f32 v[168:169], v[168:169], v[160:161]
	v_pk_mul_f32 v[170:171], v[170:171], v[162:163]
	v_cvt_pk_bf16_f32 v164, v164, v165
	v_cvt_pk_bf16_f32 v165, v166, v167
	v_cvt_pk_bf16_f32 v166, v168, v169
	v_cvt_pk_bf16_f32 v167, v170, v171
	global_store_dwordx4 v[172:173], v[164:167], off
	v_cmp_gt_f32_e32 vcc, 0x800000, v138
	v_mul_f32_e32 v141, 0x4b800000, v138
	v_pk_mul_f32 v[164:165], v[44:45], v[12:13]
	v_cndmask_b32_e32 v141, v138, v141, vcc
	v_pk_mul_f32 v[166:167], v[46:47], v[14:15]
	v_rsq_f32_e32 v141, v141
	v_pk_mul_f32 v[168:169], v[40:41], v[8:9]
	v_pk_mul_f32 v[170:171], v[42:43], v[10:11]
	v_mul_f32_e32 v140, 0x45800000, v141
	v_cndmask_b32_e32 v140, v141, v140, vcc
	v_mul_f32_e32 v140, 0xbfb8aa3b, v140
	v_pk_mul_f32 v[156:157], v[44:45], v[140:141] op_sel_hi:[1,0]
	v_pk_mul_f32 v[158:159], v[46:47], v[140:141] op_sel_hi:[1,0]
	v_pk_mul_f32 v[160:161], v[40:41], v[140:141] op_sel_hi:[1,0]
	v_pk_mul_f32 v[162:163], v[42:43], v[140:141] op_sel_hi:[1,0]
	v_exp_f32_e32 v156, v156
	v_exp_f32_e32 v157, v157
	v_exp_f32_e32 v158, v158
	v_exp_f32_e32 v159, v159
	v_exp_f32_e32 v160, v160
	v_exp_f32_e32 v161, v161
	v_exp_f32_e32 v162, v162
	v_exp_f32_e32 v163, v163
	v_pk_fma_f32 v[156:157], v[156:157], v[138:139], v[138:139] op_sel_hi:[1,0,0]
	v_pk_fma_f32 v[158:159], v[158:159], v[138:139], v[138:139] op_sel_hi:[1,0,0]
	v_pk_fma_f32 v[160:161], v[160:161], v[138:139], v[138:139] op_sel_hi:[1,0,0]
	v_pk_fma_f32 v[162:163], v[162:163], v[138:139], v[138:139] op_sel_hi:[1,0,0]
	v_rcp_f32_e32 v156, v156
	v_rcp_f32_e32 v157, v157
	v_rcp_f32_e32 v158, v158
	v_rcp_f32_e32 v159, v159
	v_rcp_f32_e32 v160, v160
	v_rcp_f32_e32 v161, v161
	v_rcp_f32_e32 v162, v162
	v_rcp_f32_e32 v163, v163
	v_lshl_add_u64 v[172:173], v[172:173], 0, s[20:21]
	v_pk_mul_f32 v[164:165], v[164:165], v[156:157]
	v_pk_mul_f32 v[166:167], v[166:167], v[158:159]
	v_pk_mul_f32 v[168:169], v[168:169], v[160:161]
	v_pk_mul_f32 v[170:171], v[170:171], v[162:163]
	v_cvt_pk_bf16_f32 v164, v164, v165
	v_cvt_pk_bf16_f32 v165, v166, v167
	v_cvt_pk_bf16_f32 v166, v168, v169
	v_cvt_pk_bf16_f32 v167, v170, v171
	global_store_dwordx4 v[172:173], v[164:167], off
	v_cmp_gt_f32_e32 vcc, 0x800000, v139
	v_mul_f32_e32 v141, 0x4b800000, v139
	v_pk_mul_f32 v[164:165], v[36:37], v[4:5]
	v_cndmask_b32_e32 v141, v139, v141, vcc
	v_pk_mul_f32 v[166:167], v[38:39], v[6:7]
	v_rsq_f32_e32 v141, v141
	v_pk_mul_f32 v[168:169], v[32:33], v[0:1]
	v_pk_mul_f32 v[170:171], v[34:35], v[2:3]
	v_mul_f32_e32 v140, 0x45800000, v141
	v_cndmask_b32_e32 v140, v141, v140, vcc
	v_mul_f32_e32 v140, 0xbfb8aa3b, v140
	v_pk_mul_f32 v[156:157], v[36:37], v[140:141] op_sel_hi:[1,0]
	v_pk_mul_f32 v[158:159], v[38:39], v[140:141] op_sel_hi:[1,0]
	v_pk_mul_f32 v[160:161], v[32:33], v[140:141] op_sel_hi:[1,0]
	v_pk_mul_f32 v[162:163], v[34:35], v[140:141] op_sel_hi:[1,0]
	v_exp_f32_e32 v156, v156
	v_exp_f32_e32 v157, v157
	v_exp_f32_e32 v158, v158
	v_exp_f32_e32 v159, v159
	v_exp_f32_e32 v160, v160
	v_exp_f32_e32 v161, v161
	v_exp_f32_e32 v162, v162
	v_exp_f32_e32 v163, v163
	v_pk_fma_f32 v[156:157], v[156:157], v[138:139], v[138:139] op_sel:[0,1,1] op_sel_hi:[1,1,1]
	v_pk_fma_f32 v[158:159], v[158:159], v[138:139], v[138:139] op_sel:[0,1,1] op_sel_hi:[1,1,1]
	v_pk_fma_f32 v[160:161], v[160:161], v[138:139], v[138:139] op_sel:[0,1,1] op_sel_hi:[1,1,1]
	v_pk_fma_f32 v[162:163], v[162:163], v[138:139], v[138:139] op_sel:[0,1,1] op_sel_hi:[1,1,1]
	v_rcp_f32_e32 v156, v156
	v_rcp_f32_e32 v157, v157
	v_rcp_f32_e32 v158, v158
	v_rcp_f32_e32 v159, v159
	v_rcp_f32_e32 v160, v160
	v_rcp_f32_e32 v161, v161
	v_rcp_f32_e32 v162, v162
	v_rcp_f32_e32 v163, v163
	v_lshl_add_u64 v[172:173], v[172:173], 0, s[20:21]
	v_pk_mul_f32 v[164:165], v[164:165], v[156:157]
	v_pk_mul_f32 v[166:167], v[166:167], v[158:159]
	v_pk_mul_f32 v[168:169], v[168:169], v[160:161]
	v_pk_mul_f32 v[170:171], v[170:171], v[162:163]
	v_cvt_pk_bf16_f32 v164, v164, v165
	v_cvt_pk_bf16_f32 v165, v166, v167
	v_cvt_pk_bf16_f32 v166, v168, v169
	v_cvt_pk_bf16_f32 v167, v170, v171
	global_store_dwordx4 v[172:173], v[164:167], off
	s_andn2_b64 vcc, exec, s[62:63]
	s_cbranch_vccnz .LBB0_120
	s_andn2_b64 vcc, exec, s[6:7]
	s_cbranch_vccnz .LBB0_110
	s_barrier
	s_branch .LBB0_110
